# previous + the XCD leader no longer bumps (and waits for) the now-unused per-XCD generation word
# speedup vs baseline: 1.0269x; 1.0014x over previous
; __device__ __forceinline__ unsigned xb_ld(unsigned* p)              { return __hip_atomic_load(p, __ATOMIC_RELAXED, __HIP_MEMORY_SCOPE_AGENT); }
; __device__ __forceinline__ unsigned xb_add(unsigned* p, unsigned v) { return __hip_atomic_fetch_add(p, v, __ATOMIC_RELAXED, __HIP_MEMORY_SCOPE_AGENT); }
; #define XB_SPIN(cond, bar) do { unsigned _sp = 0; while (cond) { __builtin_amdgcn_s_sleep(1); \
;     if ((++_sp & 255u) == 0u) { if (xb_ld(&(bar)[XB_TMO])) break; if (_sp > XB_SPIN_CAP) { atomicAdd(&(bar)[XB_TMO], 1u); break; } } } } while (0)
; __device__ __forceinline__ void xcd_barrier(const XcdBarrier& b) {
;     ...
;             const unsigned og = xb_add(&bar[XB_TOP], 1u);
;             const unsigned tg = og / nx;
;             if (og + 1u == (tg + 1u) * nx) xb_add(&bar[XB_TOPGEN], 1u);
;             else XB_SPIN(xb_ld(&bar[XB_TOPGEN]) == tg, bar);
;             __builtin_amdgcn_fence(__ATOMIC_ACQUIRE, "agent");
;             xb_add(&bar[XB_XGEN(b.x)], 1u);
;             asm volatile("s_waitcnt vmcnt(0)" ::: "memory");
.LBB0_483:
	s_or_b64 exec, exec, s[34:35]
	s_mov_b64 s[34:35], exec
	v_mbcnt_lo_u32_b32 v0, s34, 0
	v_mbcnt_hi_u32_b32 v0, s35, v0
	v_cmp_eq_u32_e32 vcc, 0, v0
	s_waitcnt vmcnt(0)
	buffer_inv sc1
	s_and_saveexec_b64 s[38:39], vcc
	s_cbranch_execz .LBB0_485
	s_bcnt1_i32_b64 s2, s[34:35]
	v_mov_b32_e32 v0, s2
.LBB0_485:
	s_or_b64 exec, exec, s[38:39]
	s_waitcnt vmcnt(0)
